# sample-attn softmax: 12 serial ds_bpermute butterfly steps replaced by DPP row reduce + readlane cross-row combine
# speedup vs baseline: 1.0051x; 1.0044x over previous
.LBB0_754:
	s_or_b64 exec, exec, s[10:11]
	s_bitset1_b32 s4, 14
	s_ashr_i32 s10, s16, 6
	s_mul_i32 s12, s4, 0x600
	s_mul_hi_u32 s11, s4, 0x600
	s_add_u32 s12, s26, s12
	s_addc_u32 s13, s27, s11
	v_lshl_add_u64 v[0:1], v[8:9], 1, s[12:13]
	s_mov_b32 s11, 0x6a80000
	v_add_co_u32_e32 v0, vcc, s11, v0
	v_readlane_b32 s17, v255, 53
	s_nop 0
	v_addc_co_u32_e32 v1, vcc, 0, v1, vcc
	v_lshl_add_u32 v1, v8, 2, s17
	s_add_i32 s11, s10, 1
	v_and_b32_e32 v64, 63, v8
	v_mov_b32_e32 v0, v209
	v_lshlrev_b32_e32 v0, 16, v0
	ds_write_b32 v1, v0
	v_cvt_f32_i32_e32 v0, s11
	s_mov_b32 s11, 0x42fc0000
	s_waitcnt lgkmcnt(0)
	s_barrier
	v_cmp_lt_f32_e32 vcc, s11, v0
	s_and_b64 s[12:13], vcc, exec
	s_cselect_b32 s11, 0xffffffc0, 0
	v_cndmask_b32_e32 v1, 0, v242, vcc
	s_add_i32 s12, s10, s58
	v_sub_f32_e32 v0, v1, v0
	s_ashr_i32 s13, s12, 31
	v_exp_f32_e32 v0, v0
	s_lshl_b64 s[12:13], s[12:13], 2
	s_add_u32 s12, s22, s12
	s_addc_u32 s13, s23, s13
	global_load_dword v65, v175, s[12:13]
	s_and_b32 s12, s16, 0xffffff00
	s_and_b32 s24, s16, 0xffffffc0
	v_ldexp_f32 v0, v0, s11
	s_add_i32 s11, s12, 0
	s_lshl_b32 s13, s24, 2
	s_add_i32 s13, s17, s13
	v_mul_f32_e32 v66, 0x3fb8aa3b, v0
	v_mov_b32_e32 v0, s11
	v_mad_u32_u24 v67, v64, s72, v0
	v_mov_b32_e32 v44, s13
	ds_read_b128 v[28:31], v44
	ds_read_b128 v[8:11], v44 offset:16
	ds_read_b128 v[4:7], v44 offset:32
	ds_read_b128 v[0:3], v44 offset:48
	ds_read_b128 v[24:27], v44 offset:64
	ds_read_b128 v[16:19], v44 offset:80
	ds_read_b128 v[20:23], v44 offset:96
	ds_read_b128 v[12:15], v44 offset:112
	ds_read_b128 v[48:51], v44 offset:128
	ds_read_b128 v[32:35], v44 offset:144
	ds_read_b128 v[52:55], v44 offset:160
	ds_read_b128 v[36:39], v44 offset:176
	ds_read_b128 v[56:59], v44 offset:192
	ds_read_b128 v[40:43], v44 offset:208
	ds_read_b128 v[60:63], v44 offset:224
	ds_read_b128 v[44:47], v44 offset:240
	s_add_i32 s13, s11, 0x10800
	v_mov_b32_e32 v184, s13
	v_cmp_eq_u32_e32 vcc, 0, v64
	ds_read_b128 v[116:119], v67
	ds_read_b128 v[120:123], v67 offset:16
	ds_read_b128 v[124:127], v67 offset:32
	ds_read_b128 v[128:131], v67 offset:48
	ds_read_b128 v[132:135], v67 offset:64
	ds_read_b128 v[136:139], v67 offset:80
	ds_read_b128 v[140:143], v67 offset:96
	ds_read_b128 v[144:147], v67 offset:112
	ds_read_b128 v[148:151], v67 offset:128
	ds_read_b128 v[152:155], v67 offset:144
	ds_read_b128 v[156:159], v67 offset:160
	ds_read_b128 v[160:163], v67 offset:176
	v_sub_u32_e32 v69, 0x80, v64
	v_cvt_f32_ubyte0_e32 v69, v69
	v_or_b32_e32 v70, 64, v64
	v_sub_u32_e32 v70, 0x80, v70
	v_cvt_f32_ubyte0_e32 v70, v70
	s_waitcnt lgkmcnt(11)
	v_pk_mul_f32 v[186:187], v[28:29], v[116:117]
	v_pk_mul_f32 v[188:189], v[30:31], v[118:119]
	ds_read_b128 v[116:119], v67 offset:192
	s_waitcnt lgkmcnt(11)
	v_pk_fma_f32 v[186:187], v[8:9], v[120:121], v[186:187]
	v_pk_fma_f32 v[188:189], v[10:11], v[122:123], v[188:189]
	ds_read_b128 v[120:123], v67 offset:208
	s_waitcnt lgkmcnt(11)
	v_pk_fma_f32 v[186:187], v[4:5], v[124:125], v[186:187]
	v_pk_fma_f32 v[188:189], v[6:7], v[126:127], v[188:189]
	ds_read_b128 v[124:127], v67 offset:224
	s_waitcnt lgkmcnt(11)
	v_pk_fma_f32 v[186:187], v[0:1], v[128:129], v[186:187]
	v_pk_fma_f32 v[188:189], v[2:3], v[130:131], v[188:189]
	ds_read_b128 v[128:131], v67 offset:240
	s_waitcnt lgkmcnt(11)
	v_pk_fma_f32 v[186:187], v[24:25], v[132:133], v[186:187]
	v_pk_fma_f32 v[188:189], v[26:27], v[134:135], v[188:189]
	ds_read_b128 v[132:135], v67 offset:33792
	s_waitcnt lgkmcnt(11)
	v_pk_fma_f32 v[186:187], v[16:17], v[136:137], v[186:187]
	v_pk_fma_f32 v[188:189], v[18:19], v[138:139], v[188:189]
	ds_read_b128 v[136:139], v67 offset:33808
	s_waitcnt lgkmcnt(11)
	v_pk_fma_f32 v[186:187], v[20:21], v[140:141], v[186:187]
	v_pk_fma_f32 v[188:189], v[22:23], v[142:143], v[188:189]
	ds_read_b128 v[140:143], v67 offset:33824
	s_waitcnt lgkmcnt(11)
	v_pk_fma_f32 v[186:187], v[12:13], v[144:145], v[186:187]
	v_pk_fma_f32 v[188:189], v[14:15], v[146:147], v[188:189]
	ds_read_b128 v[144:147], v67 offset:33840
	s_waitcnt lgkmcnt(11)
	v_pk_fma_f32 v[186:187], v[48:49], v[148:149], v[186:187]
	v_pk_fma_f32 v[188:189], v[50:51], v[150:151], v[188:189]
	ds_read_b128 v[148:151], v67 offset:33856
	s_waitcnt lgkmcnt(11)
	v_pk_fma_f32 v[186:187], v[32:33], v[152:153], v[186:187]
	v_pk_fma_f32 v[188:189], v[34:35], v[154:155], v[188:189]
	ds_read_b128 v[152:155], v67 offset:33872
	s_waitcnt lgkmcnt(11)
	v_pk_fma_f32 v[186:187], v[52:53], v[156:157], v[186:187]
	v_pk_fma_f32 v[188:189], v[54:55], v[158:159], v[188:189]
	ds_read_b128 v[156:159], v67 offset:33888
	s_waitcnt lgkmcnt(11)
	v_pk_fma_f32 v[186:187], v[36:37], v[160:161], v[186:187]
	v_pk_fma_f32 v[188:189], v[38:39], v[162:163], v[188:189]
	ds_read_b128 v[160:163], v67 offset:33904
	s_waitcnt lgkmcnt(11)
	v_pk_fma_f32 v[186:187], v[56:57], v[116:117], v[186:187]
	v_pk_fma_f32 v[188:189], v[58:59], v[118:119], v[188:189]
	ds_read_b128 v[116:119], v67 offset:33920
	s_waitcnt lgkmcnt(11)
	v_pk_fma_f32 v[186:187], v[40:41], v[120:121], v[186:187]
	v_pk_fma_f32 v[188:189], v[42:43], v[122:123], v[188:189]
	ds_read_b128 v[120:123], v67 offset:33936
	s_waitcnt lgkmcnt(11)
	v_pk_fma_f32 v[186:187], v[60:61], v[124:125], v[186:187]
	v_pk_fma_f32 v[188:189], v[62:63], v[126:127], v[188:189]
	ds_read_b128 v[124:127], v67 offset:33952
	s_waitcnt lgkmcnt(11)
	v_pk_fma_f32 v[186:187], v[44:45], v[128:129], v[186:187]
	v_pk_fma_f32 v[188:189], v[46:47], v[130:131], v[188:189]
	ds_read_b128 v[128:131], v67 offset:33968
	s_waitcnt lgkmcnt(11)
	v_pk_mul_f32 v[190:191], v[28:29], v[132:133]
	v_pk_mul_f32 v[192:193], v[30:31], v[134:135]
	ds_read_b128 v[132:135], v67 offset:33984
	s_waitcnt lgkmcnt(11)
	v_pk_fma_f32 v[190:191], v[8:9], v[136:137], v[190:191]
	v_pk_fma_f32 v[192:193], v[10:11], v[138:139], v[192:193]
	ds_read_b128 v[136:139], v67 offset:34000
	s_waitcnt lgkmcnt(11)
	v_pk_fma_f32 v[190:191], v[4:5], v[140:141], v[190:191]
	v_pk_fma_f32 v[192:193], v[6:7], v[142:143], v[192:193]
	ds_read_b128 v[140:143], v67 offset:34016
	s_waitcnt lgkmcnt(11)
	v_pk_fma_f32 v[190:191], v[0:1], v[144:145], v[190:191]
	v_pk_fma_f32 v[192:193], v[2:3], v[146:147], v[192:193]
	ds_read_b128 v[144:147], v67 offset:34032
	s_waitcnt lgkmcnt(11)
	v_pk_fma_f32 v[190:191], v[24:25], v[148:149], v[190:191]
	v_pk_fma_f32 v[192:193], v[26:27], v[150:151], v[192:193]
	ds_read_b128 v[148:151], v184
	s_waitcnt lgkmcnt(11)
	v_pk_fma_f32 v[190:191], v[16:17], v[152:153], v[190:191]
	v_pk_fma_f32 v[192:193], v[18:19], v[154:155], v[192:193]
	ds_read_b128 v[152:155], v184 offset:16
	s_waitcnt lgkmcnt(11)
	v_pk_fma_f32 v[190:191], v[20:21], v[156:157], v[190:191]
	v_pk_fma_f32 v[192:193], v[22:23], v[158:159], v[192:193]
	ds_read_b128 v[156:159], v184 offset:32
	s_waitcnt lgkmcnt(11)
	v_pk_fma_f32 v[190:191], v[12:13], v[160:161], v[190:191]
	v_pk_fma_f32 v[192:193], v[14:15], v[162:163], v[192:193]
	ds_read_b128 v[160:163], v184 offset:48
	s_waitcnt lgkmcnt(11)
	v_pk_fma_f32 v[190:191], v[48:49], v[116:117], v[190:191]
	v_pk_fma_f32 v[192:193], v[50:51], v[118:119], v[192:193]
	ds_read_b128 v[116:119], v184 offset:64
	s_waitcnt lgkmcnt(11)
	v_pk_fma_f32 v[190:191], v[32:33], v[120:121], v[190:191]
	v_pk_fma_f32 v[192:193], v[34:35], v[122:123], v[192:193]
	ds_read_b128 v[120:123], v184 offset:80
	s_waitcnt lgkmcnt(11)
	v_pk_fma_f32 v[190:191], v[52:53], v[124:125], v[190:191]
	v_pk_fma_f32 v[192:193], v[54:55], v[126:127], v[192:193]
	ds_read_b128 v[124:127], v184 offset:96
	s_waitcnt lgkmcnt(11)
	v_pk_fma_f32 v[190:191], v[36:37], v[128:129], v[190:191]
	v_pk_fma_f32 v[192:193], v[38:39], v[130:131], v[192:193]
	ds_read_b128 v[128:131], v184 offset:112
	s_waitcnt lgkmcnt(11)
	v_pk_fma_f32 v[190:191], v[56:57], v[132:133], v[190:191]
	v_pk_fma_f32 v[192:193], v[58:59], v[134:135], v[192:193]
	ds_read_b128 v[132:135], v184 offset:128
	s_waitcnt lgkmcnt(11)
	v_pk_fma_f32 v[190:191], v[40:41], v[136:137], v[190:191]
	v_pk_fma_f32 v[192:193], v[42:43], v[138:139], v[192:193]
	ds_read_b128 v[136:139], v184 offset:144
	s_waitcnt lgkmcnt(11)
	v_pk_fma_f32 v[190:191], v[60:61], v[140:141], v[190:191]
	v_pk_fma_f32 v[192:193], v[62:63], v[142:143], v[192:193]
	ds_read_b128 v[140:143], v184 offset:160
	s_waitcnt lgkmcnt(11)
	v_pk_fma_f32 v[190:191], v[44:45], v[144:145], v[190:191]
	v_pk_fma_f32 v[192:193], v[46:47], v[146:147], v[192:193]
	ds_read_b128 v[144:147], v184 offset:176
	s_waitcnt lgkmcnt(11)
	v_pk_mul_f32 v[194:195], v[28:29], v[148:149]
	v_pk_mul_f32 v[196:197], v[30:31], v[150:151]
	ds_read_b128 v[148:151], v184 offset:192
	s_waitcnt lgkmcnt(11)
	v_pk_fma_f32 v[194:195], v[8:9], v[152:153], v[194:195]
	v_pk_fma_f32 v[196:197], v[10:11], v[154:155], v[196:197]
	ds_read_b128 v[152:155], v184 offset:208
	s_waitcnt lgkmcnt(11)
	v_pk_fma_f32 v[194:195], v[4:5], v[156:157], v[194:195]
	v_pk_fma_f32 v[196:197], v[6:7], v[158:159], v[196:197]
	ds_read_b128 v[156:159], v184 offset:224
	s_waitcnt lgkmcnt(11)
	v_pk_fma_f32 v[194:195], v[0:1], v[160:161], v[194:195]
	v_pk_fma_f32 v[196:197], v[2:3], v[162:163], v[196:197]
	ds_read_b128 v[160:163], v184 offset:240
	s_waitcnt lgkmcnt(11)
	v_pk_fma_f32 v[194:195], v[24:25], v[116:117], v[194:195]
	v_pk_fma_f32 v[196:197], v[26:27], v[118:119], v[196:197]
	s_waitcnt lgkmcnt(10)
	v_pk_fma_f32 v[194:195], v[16:17], v[120:121], v[194:195]
	v_pk_fma_f32 v[196:197], v[18:19], v[122:123], v[196:197]
	s_waitcnt lgkmcnt(9)
	v_pk_fma_f32 v[194:195], v[20:21], v[124:125], v[194:195]
	v_pk_fma_f32 v[196:197], v[22:23], v[126:127], v[196:197]
	s_waitcnt lgkmcnt(8)
	v_pk_fma_f32 v[194:195], v[12:13], v[128:129], v[194:195]
	v_pk_fma_f32 v[196:197], v[14:15], v[130:131], v[196:197]
	s_waitcnt lgkmcnt(7)
	v_pk_fma_f32 v[194:195], v[48:49], v[132:133], v[194:195]
	v_pk_fma_f32 v[196:197], v[50:51], v[134:135], v[196:197]
	s_waitcnt lgkmcnt(6)
	v_pk_fma_f32 v[194:195], v[32:33], v[136:137], v[194:195]
	v_pk_fma_f32 v[196:197], v[34:35], v[138:139], v[196:197]
	s_waitcnt lgkmcnt(5)
	v_pk_fma_f32 v[194:195], v[52:53], v[140:141], v[194:195]
	v_pk_fma_f32 v[196:197], v[54:55], v[142:143], v[196:197]
	s_waitcnt lgkmcnt(4)
	v_pk_fma_f32 v[194:195], v[36:37], v[144:145], v[194:195]
	v_pk_fma_f32 v[196:197], v[38:39], v[146:147], v[196:197]
	s_waitcnt lgkmcnt(3)
	v_pk_fma_f32 v[194:195], v[56:57], v[148:149], v[194:195]
	v_pk_fma_f32 v[196:197], v[58:59], v[150:151], v[196:197]
	s_waitcnt lgkmcnt(2)
	v_pk_fma_f32 v[194:195], v[40:41], v[152:153], v[194:195]
	v_pk_fma_f32 v[196:197], v[42:43], v[154:155], v[196:197]
	s_waitcnt lgkmcnt(1)
	v_pk_fma_f32 v[194:195], v[60:61], v[156:157], v[194:195]
	v_pk_fma_f32 v[196:197], v[62:63], v[158:159], v[196:197]
	s_waitcnt lgkmcnt(0)
	v_pk_fma_f32 v[194:195], v[44:45], v[160:161], v[194:195]
	v_pk_fma_f32 v[196:197], v[46:47], v[162:163], v[196:197]
	v_add_f32_e32 v186, v186, v187
	v_add_f32_e32 v188, v188, v189
	v_add_f32_e32 v68, v186, v188
	v_add_f32_e32 v190, v190, v191
	v_add_f32_e32 v192, v192, v193
	v_add_f32_e32 v67, v190, v192
	v_add_f32_e32 v194, v194, v195
	v_add_f32_e32 v196, v196, v197
	v_add_f32_e32 v71, v194, v196
	v_fma_f32 v68, -v66, v69, v68
	v_fma_f32 v67, -v66, v70, v67
	s_mul_i32 s13, s10, 0x210
	s_add_i32 s16, s13, 0
	s_add_i32 s16, s16, 0x21420
	v_mov_b32_e32 v0, v71
	v_fmac_f32_e32 v0, 0x80000000, v66
	v_cndmask_b32_e32 v2, v243, v0, vcc
	s_waitcnt vmcnt(0)
	v_mul_f32_e32 v0, 0x3fb8aa3b, v65
	v_max_f32_e32 v1, v2, v0
	v_max3_f32 v1, v68, v67, v1
	s_nop 1
	v_max_f32_dpp v1, v1, v1 quad_perm:[1,0,3,2] row_mask:0xf bank_mask:0xf
	s_nop 1
	v_max_f32_dpp v1, v1, v1 quad_perm:[2,3,0,1] row_mask:0xf bank_mask:0xf
	s_nop 1
	v_max_f32_dpp v1, v1, v1 row_half_mirror row_mask:0xf bank_mask:0xf
	s_nop 1
	v_max_f32_dpp v1, v1, v1 row_mirror row_mask:0xf bank_mask:0xf
	s_nop 1
	v_readlane_b32 s20, v1, 0
	v_readlane_b32 s21, v1, 16
	v_readlane_b32 s40, v1, 32
	v_readlane_b32 s41, v1, 48
	v_mov_b32_e32 v4, s20
	v_max_f32_e32 v4, s21, v4
	v_max_f32_e32 v4, s40, v4
	v_max_f32_e32 v1, s41, v4
	v_sub_f32_e32 v4, v68, v1
	v_exp_f32_e32 v10, v4
	v_sub_f32_e32 v11, v67, v1
	v_exp_f32_e32 v11, v11
	v_sub_f32_e32 v2, v2, v1
	v_add_f32_e32 v4, 0, v10
	v_add_f32_e32 v12, v11, v4
	v_exp_f32_e32 v4, v2
	s_nop 0
	v_add_f32_e32 v2, v4, v12
	s_nop 1
	v_add_f32_dpp v2, v2, v2 quad_perm:[1,0,3,2] row_mask:0xf bank_mask:0xf
	s_nop 1
	v_add_f32_dpp v2, v2, v2 quad_perm:[2,3,0,1] row_mask:0xf bank_mask:0xf
	s_nop 1
	v_add_f32_dpp v2, v2, v2 row_half_mirror row_mask:0xf bank_mask:0xf
	s_nop 1
	v_add_f32_dpp v2, v2, v2 row_mirror row_mask:0xf bank_mask:0xf
	s_nop 1
	v_readlane_b32 s20, v2, 0
	v_readlane_b32 s21, v2, 16
	v_readlane_b32 s40, v2, 32
	v_readlane_b32 s41, v2, 48
	v_mov_b32_e32 v3, s20
	v_add_f32_e32 v3, s21, v3
	v_add_f32_e32 v3, s40, v3
	v_add_f32_e32 v2, s41, v3
	v_mov_b32_e32 v3, 0
	v_lshl_add_u32 v5, v64, 2, s16
	ds_write2st64_b32 v5, v10, v11 offset1:1
	s_and_saveexec_b64 s[10:11], vcc
	v_mov_b32_e32 v5, s16
	ds_write_b32 v5, v4 offset:512
	s_or_b64 exec, exec, s[10:11]
	s_waitcnt lgkmcnt(0)
	s_add_i32 s10, s12, 0x10a10
	v_lshlrev_b32_e32 v149, 2, v64
	v_add_u32_e32 v149, s10, v149
	v_add_u32_e32 v150, 0x400, v149
	v_add_u32_e32 v151, 0x800, v149
	v_add_u32_e32 v152, 0xc00, v149
	s_add_i32 s11, s13, 0x21420
	v_mov_b32_e32 v148, s11
	v_mov_b32_e32 v4, 0
	ds_read_b128 v[116:119], v148
	ds_read_b128 v[120:123], v148 offset:16
	ds_read2_b32 v[124:125], v149 offset1:132
	ds_read2_b32 v[126:127], v150 offset0:8 offset1:140
	ds_read2_b32 v[128:129], v151 offset0:16 offset1:148
	ds_read2_b32 v[130:131], v152 offset0:24 offset1:156
	v_add_u32_e32 v149, 0x1080, v149
	v_add_u32_e32 v150, 0x1080, v150
	v_add_u32_e32 v151, 0x1080, v151
	v_add_u32_e32 v152, 0x1080, v152
	ds_read_b128 v[132:135], v148 offset:32
	ds_read_b128 v[136:139], v148 offset:48
	ds_read2_b32 v[140:141], v149 offset1:132
	ds_read2_b32 v[142:143], v150 offset0:8 offset1:140
	ds_read2_b32 v[144:145], v151 offset0:16 offset1:148
	ds_read2_b32 v[146:147], v152 offset0:24 offset1:156
	v_add_u32_e32 v149, 0x1080, v149
	v_add_u32_e32 v150, 0x1080, v150
	v_add_u32_e32 v151, 0x1080, v151
	v_add_u32_e32 v152, 0x1080, v152
	s_waitcnt lgkmcnt(6)
	v_fmac_f32_e32 v4, v116, v124
	v_fmac_f32_e32 v4, v117, v125
	v_fmac_f32_e32 v4, v118, v126
	v_fmac_f32_e32 v4, v119, v127
	v_fmac_f32_e32 v4, v120, v128
	v_fmac_f32_e32 v4, v121, v129
	v_fmac_f32_e32 v4, v122, v130
	v_fmac_f32_e32 v4, v123, v131
	ds_read_b128 v[116:119], v148 offset:64
	ds_read_b128 v[120:123], v148 offset:80
	ds_read2_b32 v[124:125], v149 offset1:132
	ds_read2_b32 v[126:127], v150 offset0:8 offset1:140
	ds_read2_b32 v[128:129], v151 offset0:16 offset1:148
	ds_read2_b32 v[130:131], v152 offset0:24 offset1:156
	v_add_u32_e32 v149, 0x1080, v149
	v_add_u32_e32 v150, 0x1080, v150
	v_add_u32_e32 v151, 0x1080, v151
	v_add_u32_e32 v152, 0x1080, v152
	s_waitcnt lgkmcnt(6)
	v_fmac_f32_e32 v4, v132, v140
	v_fmac_f32_e32 v4, v133, v141
	v_fmac_f32_e32 v4, v134, v142
	v_fmac_f32_e32 v4, v135, v143
	v_fmac_f32_e32 v4, v136, v144
	v_fmac_f32_e32 v4, v137, v145
	v_fmac_f32_e32 v4, v138, v146
	v_fmac_f32_e32 v4, v139, v147
	ds_read_b128 v[132:135], v148 offset:96
	ds_read_b128 v[136:139], v148 offset:112
	ds_read2_b32 v[140:141], v149 offset1:132
	ds_read2_b32 v[142:143], v150 offset0:8 offset1:140
	ds_read2_b32 v[144:145], v151 offset0:16 offset1:148
	ds_read2_b32 v[146:147], v152 offset0:24 offset1:156
	v_add_u32_e32 v149, 0x1080, v149
	v_add_u32_e32 v150, 0x1080, v150
	v_add_u32_e32 v151, 0x1080, v151
	v_add_u32_e32 v152, 0x1080, v152
	s_waitcnt lgkmcnt(6)
	v_fmac_f32_e32 v4, v116, v124
	v_fmac_f32_e32 v4, v117, v125
	v_fmac_f32_e32 v4, v118, v126
	v_fmac_f32_e32 v4, v119, v127
	v_fmac_f32_e32 v4, v120, v128
	v_fmac_f32_e32 v4, v121, v129
	v_fmac_f32_e32 v4, v122, v130
	v_fmac_f32_e32 v4, v123, v131
	ds_read_b128 v[116:119], v148 offset:128
	ds_read_b128 v[120:123], v148 offset:144
	ds_read2_b32 v[124:125], v149 offset1:132
	ds_read2_b32 v[126:127], v150 offset0:8 offset1:140
	ds_read2_b32 v[128:129], v151 offset0:16 offset1:148
	ds_read2_b32 v[130:131], v152 offset0:24 offset1:156
	v_add_u32_e32 v149, 0x1080, v149
	v_add_u32_e32 v150, 0x1080, v150
	v_add_u32_e32 v151, 0x1080, v151
	v_add_u32_e32 v152, 0x1080, v152
	s_waitcnt lgkmcnt(6)
	v_fmac_f32_e32 v4, v132, v140
	v_fmac_f32_e32 v4, v133, v141
	v_fmac_f32_e32 v4, v134, v142
	v_fmac_f32_e32 v4, v135, v143
	v_fmac_f32_e32 v4, v136, v144
	v_fmac_f32_e32 v4, v137, v145
	v_fmac_f32_e32 v4, v138, v146
	v_fmac_f32_e32 v4, v139, v147
	ds_read_b128 v[132:135], v148 offset:160
	ds_read_b128 v[136:139], v148 offset:176
	ds_read2_b32 v[140:141], v149 offset1:132
	ds_read2_b32 v[142:143], v150 offset0:8 offset1:140
	ds_read2_b32 v[144:145], v151 offset0:16 offset1:148
	ds_read2_b32 v[146:147], v152 offset0:24 offset1:156
	v_add_u32_e32 v149, 0x1080, v149
	v_add_u32_e32 v150, 0x1080, v150
	v_add_u32_e32 v151, 0x1080, v151
	v_add_u32_e32 v152, 0x1080, v152
	s_waitcnt lgkmcnt(6)
	v_fmac_f32_e32 v4, v116, v124
	v_fmac_f32_e32 v4, v117, v125
	v_fmac_f32_e32 v4, v118, v126
	v_fmac_f32_e32 v4, v119, v127
	v_fmac_f32_e32 v4, v120, v128
	v_fmac_f32_e32 v4, v121, v129
	v_fmac_f32_e32 v4, v122, v130
	v_fmac_f32_e32 v4, v123, v131
	ds_read_b128 v[116:119], v148 offset:192
	ds_read_b128 v[120:123], v148 offset:208
	ds_read2_b32 v[124:125], v149 offset1:132
	ds_read2_b32 v[126:127], v150 offset0:8 offset1:140
	ds_read2_b32 v[128:129], v151 offset0:16 offset1:148
	ds_read2_b32 v[130:131], v152 offset0:24 offset1:156
	v_add_u32_e32 v149, 0x1080, v149
	v_add_u32_e32 v150, 0x1080, v150
	v_add_u32_e32 v151, 0x1080, v151
	v_add_u32_e32 v152, 0x1080, v152
	s_waitcnt lgkmcnt(6)
	v_fmac_f32_e32 v4, v132, v140
	v_fmac_f32_e32 v4, v133, v141
	v_fmac_f32_e32 v4, v134, v142
	v_fmac_f32_e32 v4, v135, v143
	v_fmac_f32_e32 v4, v136, v144
	v_fmac_f32_e32 v4, v137, v145
	v_fmac_f32_e32 v4, v138, v146
	v_fmac_f32_e32 v4, v139, v147
	ds_read_b128 v[132:135], v148 offset:224
	ds_read_b128 v[136:139], v148 offset:240
	ds_read2_b32 v[140:141], v149 offset1:132
	ds_read2_b32 v[142:143], v150 offset0:8 offset1:140
	ds_read2_b32 v[144:145], v151 offset0:16 offset1:148
	ds_read2_b32 v[146:147], v152 offset0:24 offset1:156
	v_add_u32_e32 v149, 0x1080, v149
	v_add_u32_e32 v150, 0x1080, v150
	v_add_u32_e32 v151, 0x1080, v151
	v_add_u32_e32 v152, 0x1080, v152
	s_waitcnt lgkmcnt(6)
	v_fmac_f32_e32 v4, v116, v124
	v_fmac_f32_e32 v4, v117, v125
	v_fmac_f32_e32 v4, v118, v126
	v_fmac_f32_e32 v4, v119, v127
	v_fmac_f32_e32 v4, v120, v128
	v_fmac_f32_e32 v4, v121, v129
	v_fmac_f32_e32 v4, v122, v130
	v_fmac_f32_e32 v4, v123, v131
	ds_read_b128 v[116:119], v148 offset:256
	ds_read_b128 v[120:123], v148 offset:272
	ds_read2_b32 v[124:125], v149 offset1:132
	ds_read2_b32 v[126:127], v150 offset0:8 offset1:140
	ds_read2_b32 v[128:129], v151 offset0:16 offset1:148
	ds_read2_b32 v[130:131], v152 offset0:24 offset1:156
	v_add_u32_e32 v149, 0x1080, v149
	v_add_u32_e32 v150, 0x1080, v150
	v_add_u32_e32 v151, 0x1080, v151
	v_add_u32_e32 v152, 0x1080, v152
	s_waitcnt lgkmcnt(6)
	v_fmac_f32_e32 v4, v132, v140
	v_fmac_f32_e32 v4, v133, v141
	v_fmac_f32_e32 v4, v134, v142
	v_fmac_f32_e32 v4, v135, v143
	v_fmac_f32_e32 v4, v136, v144
	v_fmac_f32_e32 v4, v137, v145
	v_fmac_f32_e32 v4, v138, v146
	v_fmac_f32_e32 v4, v139, v147
	ds_read_b128 v[132:135], v148 offset:288
	ds_read_b128 v[136:139], v148 offset:304
	ds_read2_b32 v[140:141], v149 offset1:132
	ds_read2_b32 v[142:143], v150 offset0:8 offset1:140
	ds_read2_b32 v[144:145], v151 offset0:16 offset1:148
	ds_read2_b32 v[146:147], v152 offset0:24 offset1:156
	v_add_u32_e32 v149, 0x1080, v149
	v_add_u32_e32 v150, 0x1080, v150
	v_add_u32_e32 v151, 0x1080, v151
	v_add_u32_e32 v152, 0x1080, v152
	s_waitcnt lgkmcnt(6)
	v_fmac_f32_e32 v4, v116, v124
	v_fmac_f32_e32 v4, v117, v125
	v_fmac_f32_e32 v4, v118, v126
	v_fmac_f32_e32 v4, v119, v127
	v_fmac_f32_e32 v4, v120, v128
	v_fmac_f32_e32 v4, v121, v129
	v_fmac_f32_e32 v4, v122, v130
	v_fmac_f32_e32 v4, v123, v131
	ds_read_b128 v[116:119], v148 offset:320
	ds_read_b128 v[120:123], v148 offset:336
	ds_read2_b32 v[124:125], v149 offset1:132
	ds_read2_b32 v[126:127], v150 offset0:8 offset1:140
	ds_read2_b32 v[128:129], v151 offset0:16 offset1:148
	ds_read2_b32 v[130:131], v152 offset0:24 offset1:156
	v_add_u32_e32 v149, 0x1080, v149
	v_add_u32_e32 v150, 0x1080, v150
	v_add_u32_e32 v151, 0x1080, v151
	v_add_u32_e32 v152, 0x1080, v152
	s_waitcnt lgkmcnt(6)
	v_fmac_f32_e32 v4, v132, v140
	v_fmac_f32_e32 v4, v133, v141
	v_fmac_f32_e32 v4, v134, v142
	v_fmac_f32_e32 v4, v135, v143
	v_fmac_f32_e32 v4, v136, v144
	v_fmac_f32_e32 v4, v137, v145
	v_fmac_f32_e32 v4, v138, v146
	v_fmac_f32_e32 v4, v139, v147
	ds_read_b128 v[132:135], v148 offset:352
	ds_read_b128 v[136:139], v148 offset:368
	ds_read2_b32 v[140:141], v149 offset1:132
	ds_read2_b32 v[142:143], v150 offset0:8 offset1:140
	ds_read2_b32 v[144:145], v151 offset0:16 offset1:148
	ds_read2_b32 v[146:147], v152 offset0:24 offset1:156
	v_add_u32_e32 v149, 0x1080, v149
	v_add_u32_e32 v150, 0x1080, v150
	v_add_u32_e32 v151, 0x1080, v151
	v_add_u32_e32 v152, 0x1080, v152
	s_waitcnt lgkmcnt(6)
	v_fmac_f32_e32 v4, v116, v124
	v_fmac_f32_e32 v4, v117, v125
	v_fmac_f32_e32 v4, v118, v126
	v_fmac_f32_e32 v4, v119, v127
	v_fmac_f32_e32 v4, v120, v128
	v_fmac_f32_e32 v4, v121, v129
	v_fmac_f32_e32 v4, v122, v130
	v_fmac_f32_e32 v4, v123, v131
	ds_read_b128 v[116:119], v148 offset:384
	ds_read_b128 v[120:123], v148 offset:400
	ds_read2_b32 v[124:125], v149 offset1:132
	ds_read2_b32 v[126:127], v150 offset0:8 offset1:140
	ds_read2_b32 v[128:129], v151 offset0:16 offset1:148
	ds_read2_b32 v[130:131], v152 offset0:24 offset1:156
	v_add_u32_e32 v149, 0x1080, v149
	v_add_u32_e32 v150, 0x1080, v150
	v_add_u32_e32 v151, 0x1080, v151
	v_add_u32_e32 v152, 0x1080, v152
	s_waitcnt lgkmcnt(6)
	v_fmac_f32_e32 v4, v132, v140
	v_fmac_f32_e32 v4, v133, v141
	v_fmac_f32_e32 v4, v134, v142
	v_fmac_f32_e32 v4, v135, v143
	v_fmac_f32_e32 v4, v136, v144
	v_fmac_f32_e32 v4, v137, v145
	v_fmac_f32_e32 v4, v138, v146
	v_fmac_f32_e32 v4, v139, v147
	ds_read_b128 v[132:135], v148 offset:416
	ds_read_b128 v[136:139], v148 offset:432
	ds_read2_b32 v[140:141], v149 offset1:132
	ds_read2_b32 v[142:143], v150 offset0:8 offset1:140
	ds_read2_b32 v[144:145], v151 offset0:16 offset1:148
	ds_read2_b32 v[146:147], v152 offset0:24 offset1:156
	v_add_u32_e32 v149, 0x1080, v149
	v_add_u32_e32 v150, 0x1080, v150
	v_add_u32_e32 v151, 0x1080, v151
	v_add_u32_e32 v152, 0x1080, v152
	s_waitcnt lgkmcnt(6)
	v_fmac_f32_e32 v4, v116, v124
	v_fmac_f32_e32 v4, v117, v125
	v_fmac_f32_e32 v4, v118, v126
	v_fmac_f32_e32 v4, v119, v127
	v_fmac_f32_e32 v4, v120, v128
	v_fmac_f32_e32 v4, v121, v129
	v_fmac_f32_e32 v4, v122, v130
	v_fmac_f32_e32 v4, v123, v131
	ds_read_b128 v[116:119], v148 offset:448
	ds_read_b128 v[120:123], v148 offset:464
	ds_read2_b32 v[124:125], v149 offset1:132
	ds_read2_b32 v[126:127], v150 offset0:8 offset1:140
	ds_read2_b32 v[128:129], v151 offset0:16 offset1:148
	ds_read2_b32 v[130:131], v152 offset0:24 offset1:156
	v_add_u32_e32 v149, 0x1080, v149
	v_add_u32_e32 v150, 0x1080, v150
	v_add_u32_e32 v151, 0x1080, v151
	v_add_u32_e32 v152, 0x1080, v152
	s_waitcnt lgkmcnt(6)
	v_fmac_f32_e32 v4, v132, v140
	v_fmac_f32_e32 v4, v133, v141
	v_fmac_f32_e32 v4, v134, v142
	v_fmac_f32_e32 v4, v135, v143
	v_fmac_f32_e32 v4, v136, v144
	v_fmac_f32_e32 v4, v137, v145
	v_fmac_f32_e32 v4, v138, v146
	v_fmac_f32_e32 v4, v139, v147
	ds_read_b128 v[132:135], v148 offset:480
	ds_read_b128 v[136:139], v148 offset:496
	ds_read2_b32 v[140:141], v149 offset1:132
	ds_read2_b32 v[142:143], v150 offset0:8 offset1:140
	ds_read2_b32 v[144:145], v151 offset0:16 offset1:148
	ds_read2_b32 v[146:147], v152 offset0:24 offset1:156
	v_add_u32_e32 v149, 0x1080, v149
	v_add_u32_e32 v150, 0x1080, v150
	v_add_u32_e32 v151, 0x1080, v151
	v_add_u32_e32 v152, 0x1080, v152
	s_waitcnt lgkmcnt(6)
	v_fmac_f32_e32 v4, v116, v124
	v_fmac_f32_e32 v4, v117, v125
	v_fmac_f32_e32 v4, v118, v126
	v_fmac_f32_e32 v4, v119, v127
	v_fmac_f32_e32 v4, v120, v128
	v_fmac_f32_e32 v4, v121, v129
	v_fmac_f32_e32 v4, v122, v130
	v_fmac_f32_e32 v4, v123, v131
	ds_read_b32 v153, v148 offset:512
	ds_read_b32 v154, v149
	s_waitcnt lgkmcnt(2)
	v_fmac_f32_e32 v4, v132, v140
	v_fmac_f32_e32 v4, v133, v141
	v_fmac_f32_e32 v4, v134, v142
	v_fmac_f32_e32 v4, v135, v143
	v_fmac_f32_e32 v4, v136, v144
	v_fmac_f32_e32 v4, v137, v145
	v_fmac_f32_e32 v4, v138, v146
	v_fmac_f32_e32 v4, v139, v147
	s_waitcnt lgkmcnt(0)
	v_fmac_f32_e32 v4, v153, v154
